# v3 with K-loop heads padded to the baseline's byte offsets mod 128
# baseline (speedup 1.0000x reference)
.LBB0_120:
	s_lshl_b32 s49, s48, 19
	s_or_b32 s50, s52, 0x700
	s_and_b64 s[16:17], s[4:5], exec
	s_cselect_b32 s16, s49, s50
	s_lshl_b32 s50, s47, 19
	s_or_b32 s17, s53, 0x700
	s_and_b64 s[54:55], s[4:5], exec
	v_mov_b32_e32 v2, 0
	s_cselect_b32 s17, s50, s17
	s_add_i32 s52, s52, 0x40080
	s_addk_i32 s53, 0x100
	s_mov_b32 s54, -2
	v_mov_b32_e32 v3, v2
	v_mov_b32_e32 v4, v2
	v_mov_b32_e32 v5, v2
	v_mov_b32_e32 v6, v2
	v_mov_b32_e32 v7, v2
	v_mov_b32_e32 v8, v2
	v_mov_b32_e32 v9, v2
	v_mov_b32_e32 v10, v2
	v_mov_b32_e32 v11, v2
	v_mov_b32_e32 v12, v2
	v_mov_b32_e32 v13, v2
	v_mov_b32_e32 v18, v2
	v_mov_b32_e32 v19, v2
	v_mov_b32_e32 v20, v2
	v_mov_b32_e32 v21, v2
	v_mov_b32_e32 v26, v2
	v_mov_b32_e32 v27, v2
	v_mov_b32_e32 v28, v2
	v_mov_b32_e32 v29, v2
	v_mov_b32_e32 v34, v2
	v_mov_b32_e32 v35, v2
	v_mov_b32_e32 v36, v2
	v_mov_b32_e32 v37, v2
	v_mov_b32_e32 v42, v2
	v_mov_b32_e32 v43, v2
	v_mov_b32_e32 v44, v2
	v_mov_b32_e32 v45, v2
	v_mov_b32_e32 v50, v2
	v_mov_b32_e32 v51, v2
	v_mov_b32_e32 v52, v2
	v_mov_b32_e32 v53, v2
	v_mov_b32_e32 v14, v2
	v_mov_b32_e32 v15, v2
	v_mov_b32_e32 v16, v2
	v_mov_b32_e32 v17, v2
	v_mov_b32_e32 v22, v2
	v_mov_b32_e32 v23, v2
	v_mov_b32_e32 v24, v2
	v_mov_b32_e32 v25, v2
	v_mov_b32_e32 v30, v2
	v_mov_b32_e32 v31, v2
	v_mov_b32_e32 v32, v2
	v_mov_b32_e32 v33, v2
	v_mov_b32_e32 v38, v2
	v_mov_b32_e32 v39, v2
	v_mov_b32_e32 v40, v2
	v_mov_b32_e32 v41, v2
	v_mov_b32_e32 v46, v2
	v_mov_b32_e32 v47, v2
	v_mov_b32_e32 v48, v2
	v_mov_b32_e32 v49, v2
	v_mov_b32_e32 v54, v2
	v_mov_b32_e32 v55, v2
	v_mov_b32_e32 v56, v2
	v_mov_b32_e32 v57, v2
	v_mov_b32_e32 v58, v2
	v_mov_b32_e32 v59, v2
	v_mov_b32_e32 v60, v2
	v_mov_b32_e32 v61, v2
	v_mov_b32_e32 v62, v2
	v_mov_b32_e32 v63, v2
	v_mov_b32_e32 v64, v2
	v_mov_b32_e32 v65, v2
	v_mov_b32_e32 v66, v2
	v_mov_b32_e32 v67, v2
	v_mov_b32_e32 v68, v2
	v_mov_b32_e32 v69, v2
	v_mov_b32_e32 v70, v2
	v_mov_b32_e32 v71, v2
	v_mov_b32_e32 v72, v2
	v_mov_b32_e32 v73, v2
	v_mov_b32_e32 v74, v2
	v_mov_b32_e32 v75, v2
	v_mov_b32_e32 v76, v2
	v_mov_b32_e32 v77, v2
	v_mov_b32_e32 v82, v2
	v_mov_b32_e32 v83, v2
	v_mov_b32_e32 v84, v2
	v_mov_b32_e32 v85, v2
	v_mov_b32_e32 v90, v2
	v_mov_b32_e32 v91, v2
	v_mov_b32_e32 v92, v2
	v_mov_b32_e32 v93, v2
	v_mov_b32_e32 v98, v2
	v_mov_b32_e32 v99, v2
	v_mov_b32_e32 v100, v2
	v_mov_b32_e32 v101, v2
	v_mov_b32_e32 v106, v2
	v_mov_b32_e32 v107, v2
	v_mov_b32_e32 v108, v2
	v_mov_b32_e32 v109, v2
	v_mov_b32_e32 v114, v2
	v_mov_b32_e32 v115, v2
	v_mov_b32_e32 v116, v2
	v_mov_b32_e32 v117, v2
	v_mov_b32_e32 v78, v2
	v_mov_b32_e32 v79, v2
	v_mov_b32_e32 v80, v2
	v_mov_b32_e32 v81, v2
	v_mov_b32_e32 v86, v2
	v_mov_b32_e32 v87, v2
	v_mov_b32_e32 v88, v2
	v_mov_b32_e32 v89, v2
	v_mov_b32_e32 v94, v2
	v_mov_b32_e32 v95, v2
	v_mov_b32_e32 v96, v2
	v_mov_b32_e32 v97, v2
	v_mov_b32_e32 v102, v2
	v_mov_b32_e32 v103, v2
	v_mov_b32_e32 v104, v2
	v_mov_b32_e32 v105, v2
	v_mov_b32_e32 v110, v2
	v_mov_b32_e32 v111, v2
	v_mov_b32_e32 v112, v2
	v_mov_b32_e32 v113, v2
	v_mov_b32_e32 v118, v2
	v_mov_b32_e32 v119, v2
	v_mov_b32_e32 v120, v2
	v_mov_b32_e32 v121, v2
	v_mov_b32_e32 v122, v2
	v_mov_b32_e32 v123, v2
	v_mov_b32_e32 v124, v2
	v_mov_b32_e32 v125, v2
	v_mov_b32_e32 v126, v2
	v_mov_b32_e32 v127, v2
	v_mov_b32_e32 v128, v2
	v_mov_b32_e32 v129, v2
	s_nop 0
	s_nop 0

.LBB0_222:
	s_lshl_b32 s2, s53, 19
	s_or_b32 s3, s39, 0x700
	s_and_b64 s[58:59], s[6:7], exec
	s_cselect_b32 s55, s2, s3
	s_lshl_b32 s3, s52, 19
	s_or_b32 s60, s34, 0x700
	s_and_b64 s[58:59], s[6:7], exec
	s_cselect_b32 s58, s3, s60
	s_mov_b32 s59, -2
	s_movk_i32 s60, 0xf900
	s_nop 0
	s_nop 0

.LBB0_466:
	s_mov_b32 s0, -2
	s_movk_i32 s1, 0xeb00
	s_nop 0
	s_nop 0

.LBB0_618:
	s_lshl_b32 s76, s73, 18
	s_or_b32 s3, s41, 0x300
	s_and_b64 s[0:1], s[4:5], exec
	v_mov_b32_e32 v6, 0
	s_cselect_b32 s0, s76, s3
	s_add_i32 s1, s2, 0x20080
	s_add_i32 s2, s41, 0x100
	s_mov_b32 s3, -2
	v_mov_b32_e32 v7, v6
	v_mov_b32_e32 v8, v6
	v_mov_b32_e32 v9, v6
	v_mov_b32_e32 v10, v6
	v_mov_b32_e32 v11, v6
	v_mov_b32_e32 v12, v6
	v_mov_b32_e32 v13, v6
	s_waitcnt lgkmcnt(3)
	v_mov_b32_e32 v22, v6
	s_waitcnt lgkmcnt(1)
	v_mov_b32_e32 v23, v6
	v_mov_b32_e32 v24, v6
	v_mov_b32_e32 v25, v6
	v_mov_b32_e32 v26, v6
	v_mov_b32_e32 v27, v6
	v_mov_b32_e32 v28, v6
	v_mov_b32_e32 v29, v6
	s_waitcnt vmcnt(7)
	v_mov_b32_e32 v50, v6
	v_mov_b32_e32 v51, v6
	v_mov_b32_e32 v52, v6
	v_mov_b32_e32 v53, v6
	s_waitcnt vmcnt(4)
	v_mov_b32_e32 v54, v6
	v_mov_b32_e32 v55, v6
	v_mov_b32_e32 v56, v6
	v_mov_b32_e32 v57, v6
	v_mov_b32_e32 v70, v6
	v_mov_b32_e32 v71, v6
	v_mov_b32_e32 v72, v6
	v_mov_b32_e32 v73, v6
	v_mov_b32_e32 v74, v6
	v_mov_b32_e32 v75, v6
	v_mov_b32_e32 v76, v6
	v_mov_b32_e32 v77, v6
	v_mov_b32_e32 v14, v6
	v_mov_b32_e32 v15, v6
	v_mov_b32_e32 v16, v6
	v_mov_b32_e32 v17, v6
	v_mov_b32_e32 v18, v6
	v_mov_b32_e32 v19, v6
	v_mov_b32_e32 v20, v6
	s_waitcnt lgkmcnt(0)
	v_mov_b32_e32 v21, v6
	v_mov_b32_e32 v30, v6
	v_mov_b32_e32 v31, v6
	v_mov_b32_e32 v32, v6
	v_mov_b32_e32 v33, v6
	v_mov_b32_e32 v34, v6
	v_mov_b32_e32 v35, v6
	v_mov_b32_e32 v36, v6
	v_mov_b32_e32 v37, v6
	v_mov_b32_e32 v62, v6
	v_mov_b32_e32 v63, v6
	v_mov_b32_e32 v64, v6
	v_mov_b32_e32 v65, v6
	v_mov_b32_e32 v66, v6
	v_mov_b32_e32 v67, v6
	v_mov_b32_e32 v68, v6
	v_mov_b32_e32 v69, v6
	v_mov_b32_e32 v78, v6
	v_mov_b32_e32 v79, v6
	v_mov_b32_e32 v80, v6
	v_mov_b32_e32 v81, v6
	v_mov_b32_e32 v82, v6
	v_mov_b32_e32 v83, v6
	v_mov_b32_e32 v84, v6
	v_mov_b32_e32 v85, v6
	v_mov_b32_e32 v86, v6
	v_mov_b32_e32 v87, v6
	v_mov_b32_e32 v88, v6
	v_mov_b32_e32 v89, v6
	v_mov_b32_e32 v90, v6
	v_mov_b32_e32 v91, v6
	v_mov_b32_e32 v92, v6
	v_mov_b32_e32 v93, v6
	v_mov_b32_e32 v102, v6
	v_mov_b32_e32 v103, v6
	v_mov_b32_e32 v104, v6
	v_mov_b32_e32 v105, v6
	v_mov_b32_e32 v106, v6
	v_mov_b32_e32 v107, v6
	v_mov_b32_e32 v108, v6
	v_mov_b32_e32 v109, v6
	v_mov_b32_e32 v118, v6
	v_mov_b32_e32 v119, v6
	v_mov_b32_e32 v120, v6
	v_mov_b32_e32 v121, v6
	v_mov_b32_e32 v122, v6
	v_mov_b32_e32 v123, v6
	v_mov_b32_e32 v124, v6
	v_mov_b32_e32 v125, v6
	v_mov_b32_e32 v134, v6
	v_mov_b32_e32 v135, v6
	v_mov_b32_e32 v136, v6
	v_mov_b32_e32 v137, v6
	v_mov_b32_e32 v138, v6
	v_mov_b32_e32 v139, v6
	v_mov_b32_e32 v140, v6
	v_mov_b32_e32 v141, v6
	v_mov_b32_e32 v94, v6
	v_mov_b32_e32 v95, v6
	v_mov_b32_e32 v96, v6
	v_mov_b32_e32 v97, v6
	v_mov_b32_e32 v98, v6
	v_mov_b32_e32 v99, v6
	v_mov_b32_e32 v100, v6
	v_mov_b32_e32 v101, v6
	v_mov_b32_e32 v110, v6
	v_mov_b32_e32 v111, v6
	v_mov_b32_e32 v112, v6
	v_mov_b32_e32 v113, v6
	v_mov_b32_e32 v114, v6
	v_mov_b32_e32 v115, v6
	v_mov_b32_e32 v116, v6
	v_mov_b32_e32 v117, v6
	v_mov_b32_e32 v126, v6
	v_mov_b32_e32 v127, v6
	v_mov_b32_e32 v128, v6
	v_mov_b32_e32 v129, v6
	v_mov_b32_e32 v130, v6
	v_mov_b32_e32 v131, v6
	v_mov_b32_e32 v132, v6
	v_mov_b32_e32 v133, v6
	v_mov_b32_e32 v158, v6
	v_mov_b32_e32 v159, v6
	v_mov_b32_e32 v160, v6
	v_mov_b32_e32 v161, v6
	v_mov_b32_e32 v162, v6
	v_mov_b32_e32 v163, v6
	v_mov_b32_e32 v164, v6
	v_mov_b32_e32 v165, v6
	s_nop 0
	s_nop 0

.LBB0_942:
	s_lshl_b32 s0, s51, 19
	s_or_b32 s1, s37, 0x300
	s_and_b64 s[54:55], s[6:7], exec
	s_cselect_b32 s53, s0, s1
	s_lshl_b32 s1, s50, 18
	s_or_b32 s58, s33, 0x300
	s_and_b64 s[54:55], s[6:7], exec
	s_cselect_b32 s54, s1, s58
	s_mov_b32 s55, -2
	s_movk_i32 s58, 0xfd00
	s_nop 0
	s_nop 0
